# GEMM4 epilogue: final_g vectors loaded once at the top of the epilogue into free VGPRs; the two loads that sat behind the first 16 output stores (and their vmcnt waits) are gone, so all 32 stores issu
# speedup vs baseline: 1.0195x; 1.0015x over previous
.LBB0_879:
	s_or_b32 s1, s0, s47
	v_mov_b32_e32 v195, v186
	v_mov_b32_e32 v196, v185
	s_nop 15
	s_nop 15
	s_lshl_b32 s0, s1, 8
	v_add_u32_e32 v194, s55, v196
	v_lshl_add_u32 v174, v195, 3, s69
	v_add_u32_e32 v172, s0, v194
	v_ashrrev_i32_e32 v175, 31, v174
	v_ashrrev_i32_e32 v173, 31, v172
	v_lshl_add_u64 v[182:183], v[174:175], 1, s[10:11]
	v_lshlrev_b64 v[242:243], 2, v[174:175]
	v_lshl_add_u64 v[242:243], s[12:13], 0, v[242:243]
	global_load_dwordx4 v[226:229], v[242:243], off
	global_load_dwordx4 v[230:233], v[242:243], off offset:16
	global_load_dwordx4 v[234:237], v[242:243], off offset:512
	global_load_dwordx4 v[238:241], v[242:243], off offset:528
	v_lshlrev_b64 v[128:129], 12, v[172:173]
	v_lshl_add_u64 v[176:177], v[182:183], 0, v[128:129]
	global_load_dwordx4 v[178:181], v[176:177], off
	global_load_dwordx4 v[198:201], v[176:177], off offset:256
	v_add_u32_e32 v170, 16, v172
	v_add_u32_e32 v168, 32, v172
	v_add_u32_e32 v166, 48, v172
	v_ashrrev_i32_e32 v171, 31, v170
	v_ashrrev_i32_e32 v169, 31, v168
	v_ashrrev_i32_e32 v167, 31, v166
	v_lshlrev_b64 v[128:129], 12, v[170:171]
	v_lshlrev_b64 v[130:131], 12, v[168:169]
	v_lshlrev_b64 v[132:133], 12, v[166:167]
	v_lshl_add_u64 v[128:129], v[182:183], 0, v[128:129]
	v_lshl_add_u64 v[130:131], v[182:183], 0, v[130:131]
	v_lshl_add_u64 v[202:203], v[182:183], 0, v[132:133]
	global_load_dwordx4 v[148:151], v[128:129], off
	global_load_dwordx4 v[144:147], v[128:129], off offset:256
	global_load_dwordx4 v[140:143], v[130:131], off
	global_load_dwordx4 v[136:139], v[130:131], off offset:256
	global_load_dwordx4 v[132:135], v[202:203], off
	s_nop 0
	global_load_dwordx4 v[128:131], v[202:203], off offset:256
	v_and_b32_e32 v202, 64, v191
	v_add_u32_e32 v210, 64, v202
	v_xor_b32_e32 v197, 16, v191
	v_cmp_lt_i32_e32 vcc, v197, v210
	v_cmp_eq_u32_e64 s[4:5], 0, v195
	s_waitcnt vmcnt(0)
	v_lshlrev_b32_e32 v202, 16, v178
	v_and_b32_e32 v203, 0xffff0000, v178
	v_lshlrev_b32_e32 v178, 16, v179
	v_and_b32_e32 v179, 0xffff0000, v179
	v_lshlrev_b32_e32 v206, 16, v198
	v_and_b32_e32 v207, 0xffff0000, v198
	v_lshlrev_b32_e32 v198, 16, v199
	v_and_b32_e32 v199, 0xffff0000, v199
	v_lshlrev_b32_e32 v204, 16, v180
	v_and_b32_e32 v205, 0xffff0000, v180
	v_lshlrev_b32_e32 v208, 16, v200
	v_and_b32_e32 v209, 0xffff0000, v200
	v_pk_add_f32 v[126:127], v[126:127], v[178:179]
	v_pk_add_f32 v[124:125], v[124:125], v[202:203]
	v_pk_add_f32 v[118:119], v[118:119], v[198:199]
	v_pk_add_f32 v[116:117], v[116:117], v[206:207]
	v_lshlrev_b32_e32 v180, 16, v181
	v_and_b32_e32 v181, 0xffff0000, v181
	v_lshlrev_b32_e32 v200, 16, v201
	v_and_b32_e32 v201, 0xffff0000, v201
	v_pk_add_f32 v[120:121], v[120:121], v[204:205]
	v_pk_add_f32 v[112:113], v[112:113], v[208:209]
	v_mul_f32_e32 v178, v125, v125
	v_mul_f32_e32 v179, v127, v127
	v_mul_f32_e32 v198, v117, v117
	v_mul_f32_e32 v199, v119, v119
	v_pk_add_f32 v[122:123], v[122:123], v[180:181]
	v_pk_add_f32 v[114:115], v[114:115], v[200:201]
	v_mul_f32_e32 v180, v121, v121
	v_mul_f32_e32 v200, v113, v113
	v_fmac_f32_e32 v178, v124, v124
	v_fmac_f32_e32 v179, v126, v126
	v_fmac_f32_e32 v198, v116, v116
	v_fmac_f32_e32 v199, v118, v118
	v_mul_f32_e32 v181, v123, v123
	v_mul_f32_e32 v201, v115, v115
	v_fmac_f32_e32 v180, v120, v120
	v_fmac_f32_e32 v200, v112, v112
	v_add_f32_e32 v178, v178, v179
	v_add_f32_e32 v179, v198, v199
	v_fmac_f32_e32 v181, v122, v122
	v_fmac_f32_e32 v201, v114, v114
	v_add_f32_e32 v178, v180, v178
	v_add_f32_e32 v179, v200, v179
	v_cndmask_b32_e32 v197, v191, v197, vcc
	v_add_f32_e32 v178, v181, v178
	v_add_f32_e32 v179, v201, v179
	v_lshlrev_b32_e32 v197, 2, v197
	v_add_f32_e32 v178, v178, v179
	ds_bpermute_b32 v179, v197, v178
	v_xor_b32_e32 v180, 32, v191
	v_cmp_lt_i32_e32 vcc, v180, v210
	s_waitcnt lgkmcnt(0)
	v_add_f32_e32 v178, v178, v179
	v_cndmask_b32_e32 v180, v191, v180, vcc
	v_lshlrev_b32_e32 v198, 2, v180
	ds_bpermute_b32 v179, v198, v178
	s_and_saveexec_b64 s[38:39], s[4:5]
	s_cbranch_execz .LBB0_881
	s_waitcnt lgkmcnt(0)
	v_add_f32_e32 v178, v178, v179
	v_lshl_add_u32 v179, v194, 4, s60
	ds_write_b32 v179, v178

.LBB0_913:
	s_or_b64 exec, exec, s[38:39]
	v_lshlrev_b64 v[64:65], 2, v[174:175]
	s_waitcnt vmcnt(0) lgkmcnt(0)
	s_barrier
	v_lshl_add_u64 v[66:67], s[12:13], 0, v[64:65]
	s_add_i32 s1, 0, 0x21000
	v_lshlrev_b64 v[78:79], 13, v[170:171]
	v_lshl_add_u32 v199, v194, 2, s1
	v_lshl_add_u64 v[86:87], s[14:15], 0, v[78:79]
	v_lshlrev_b64 v[76:77], 13, v[172:173]
	v_lshlrev_b64 v[82:83], 13, v[168:169]
	v_lshlrev_b64 v[80:81], 13, v[166:167]
	ds_read2_b32 v[168:169], v199 offset1:16
	v_lshl_add_u64 v[172:173], v[86:87], 0, v[64:65]
	ds_read2_b32 v[166:167], v199 offset0:16 offset1:32
	ds_read2_b32 v[86:87], v199 offset0:32 offset1:48
	v_add_u32_e32 v195, 0x80, v194
	v_lshl_add_u64 v[84:85], s[14:15], 0, v[76:77]
	v_lshl_add_u32 v197, v195, 2, s1
	v_lshl_add_u64 v[170:171], v[84:85], 0, v[64:65]
	ds_read_b32 v196, v199
	ds_read_b32 v84, v199 offset:704
	ds_read_b32 v198, v197
	ds_read_b32 v200, v197
	v_add_u32_e32 v194, s0, v195
	v_ashrrev_i32_e32 v195, 31, v194
	v_lshlrev_b64 v[194:195], 13, v[194:195]
	s_waitcnt lgkmcnt(3)
	v_pk_mul_f32 v[126:127], v[126:127], v[196:197] op_sel_hi:[1,0]
	v_pk_mul_f32 v[124:125], v[124:125], v[196:197] op_sel_hi:[1,0]
	v_pk_mul_f32 v[122:123], v[122:123], v[196:197] op_sel_hi:[1,0]
	v_pk_mul_f32 v[120:121], v[120:121], v[196:197] op_sel_hi:[1,0]
	v_mov_b32_e32 v196, v169
	v_mov_b32_e32 v204, v167
	v_mov_b32_e32 v206, v87
	v_lshl_add_u64 v[174:175], s[14:15], 0, v[82:83]
	v_lshl_add_u64 v[182:183], s[14:15], 0, v[80:81]
	v_lshl_add_u64 v[202:203], s[14:15], 0, v[194:195]
	s_waitcnt lgkmcnt(1)
	v_pk_mul_f32 v[208:209], v[60:61], v[198:199] op_sel_hi:[1,0]
	v_pk_mul_f32 v[210:211], v[62:63], v[198:199] op_sel_hi:[1,0]
	v_pk_mul_f32 v[110:111], v[110:111], v[196:197] op_sel_hi:[1,0]
	v_pk_mul_f32 v[108:109], v[108:109], v[196:197] op_sel_hi:[1,0]
	v_pk_mul_f32 v[212:213], v[106:107], v[196:197] op_sel_hi:[1,0]
	v_pk_mul_f32 v[196:197], v[104:105], v[196:197] op_sel_hi:[1,0]
	v_pk_mul_f32 v[140:141], v[140:141], v[204:205] op_sel_hi:[1,0]
	v_pk_mul_f32 v[144:145], v[144:145], v[204:205] op_sel_hi:[1,0]
	v_pk_mul_f32 v[142:143], v[142:143], v[204:205] op_sel_hi:[1,0]
	v_pk_mul_f32 v[146:147], v[146:147], v[204:205] op_sel_hi:[1,0]
	v_pk_mul_f32 v[204:205], v[136:137], v[206:207] op_sel_hi:[1,0]
	v_pk_mul_f32 v[214:215], v[138:139], v[206:207] op_sel_hi:[1,0]
	v_pk_mul_f32 v[148:149], v[148:149], v[206:207] op_sel_hi:[1,0]
	v_pk_mul_f32 v[150:151], v[150:151], v[206:207] op_sel_hi:[1,0]
	v_lshl_add_u64 v[174:175], v[174:175], 0, v[64:65]
	v_lshl_add_u64 v[182:183], v[182:183], 0, v[64:65]
	v_lshl_add_u64 v[202:203], v[202:203], 0, v[64:65]
	v_pk_mul_f32 v[56:57], v[56:57], v[198:199] op_sel_hi:[1,0]
	v_pk_mul_f32 v[58:59], v[58:59], v[198:199] op_sel_hi:[1,0]
	v_pk_mul_f32 v[10:11], v[10:11], v[84:85] op_sel_hi:[1,0]
	v_pk_mul_f32 v[14:15], v[14:15], v[84:85] op_sel_hi:[1,0]
	s_and_b64 vcc, exec, s[6:7]
	s_mov_b64 s[6:7], -1
	v_pk_mul_f32 v[62:63], v[228:229], v[126:127]
	v_pk_mul_f32 v[60:61], v[226:227], v[124:125]
	v_pk_mul_f32 v[106:107], v[232:233], v[122:123]
	v_pk_mul_f32 v[104:105], v[230:231], v[120:121]
	v_pk_mul_f32 v[110:111], v[228:229], v[110:111]
	v_pk_mul_f32 v[108:109], v[226:227], v[108:109]
	v_pk_mul_f32 v[122:123], v[232:233], v[212:213]
	v_pk_mul_f32 v[120:121], v[230:231], v[196:197]
	v_pk_mul_f32 v[126:127], v[228:229], v[140:141]
	v_pk_mul_f32 v[124:125], v[226:227], v[144:145]
	v_pk_mul_f32 v[138:139], v[232:233], v[142:143]
	v_pk_mul_f32 v[136:137], v[230:231], v[146:147]
	v_pk_mul_f32 v[142:143], v[228:229], v[204:205]
	v_pk_mul_f32 v[140:141], v[226:227], v[214:215]
	v_pk_mul_f32 v[146:147], v[232:233], v[148:149]
	v_pk_mul_f32 v[144:145], v[230:231], v[150:151]
	v_pk_mul_f32 v[150:151], v[228:229], v[210:211]
	v_pk_mul_f32 v[148:149], v[226:227], v[208:209]
	global_store_dwordx4 v[170:171], v[60:63], off
	global_store_dwordx4 v[170:171], v[104:107], off offset:16
	global_store_dwordx4 v[172:173], v[108:111], off
	global_store_dwordx4 v[172:173], v[120:123], off offset:16
	global_store_dwordx4 v[174:175], v[124:127], off
	global_store_dwordx4 v[174:175], v[136:139], off offset:16
	global_store_dwordx4 v[182:183], v[140:143], off
	global_store_dwordx4 v[182:183], v[144:147], off offset:16
	global_store_dwordx4 v[202:203], v[148:151], off
	ds_read2_b32 v[104:105], v199 offset0:48 offset1:144
	ds_read2_b32 v[108:109], v199 offset0:144 offset1:160
	v_pk_mul_f32 v[58:59], v[232:233], v[58:59]
	v_pk_mul_f32 v[56:57], v[230:231], v[56:57]
	global_store_dwordx4 v[202:203], v[56:59], off offset:16
	v_lshlrev_b64 v[106:107], 13, v[180:181]
	s_waitcnt lgkmcnt(0)
	v_mov_b32_e32 v110, v109
	v_mov_b32_e32 v56, v105
	v_lshl_add_u64 v[58:59], s[14:15], 0, v[106:107]
	v_pk_mul_f32 v[42:43], v[42:43], v[56:57] op_sel_hi:[1,0]
	v_pk_mul_f32 v[40:41], v[40:41], v[56:57] op_sel_hi:[1,0]
	v_lshl_add_u64 v[58:59], v[58:59], 0, v[64:65]
	v_pk_mul_f32 v[42:43], v[232:233], v[42:43]
	v_pk_mul_f32 v[40:41], v[230:231], v[40:41]
	v_lshlrev_b64 v[120:121], 13, v[178:179]
	global_store_dwordx4 v[58:59], v[40:43], off offset:16
	v_pk_mul_f32 v[26:27], v[26:27], v[110:111] op_sel_hi:[1,0]
	v_pk_mul_f32 v[24:25], v[24:25], v[110:111] op_sel_hi:[1,0]
	v_lshl_add_u64 v[40:41], s[14:15], 0, v[120:121]
	v_lshl_add_u64 v[40:41], v[40:41], 0, v[64:65]
	v_pk_mul_f32 v[26:27], v[232:233], v[26:27]
	v_pk_mul_f32 v[24:25], v[230:231], v[24:25]
	v_pk_mul_f32 v[46:47], v[46:47], v[56:57] op_sel_hi:[1,0]
	v_pk_mul_f32 v[30:31], v[30:31], v[110:111] op_sel_hi:[1,0]
	global_store_dwordx4 v[40:41], v[24:27], off offset:16
	v_pk_mul_f32 v[44:45], v[44:45], v[56:57] op_sel_hi:[1,0]
	v_pk_mul_f32 v[46:47], v[228:229], v[46:47]
	v_pk_mul_f32 v[24:25], v[68:69], v[84:85] op_sel_hi:[1,0]
	v_lshlrev_b64 v[68:69], 13, v[176:177]
	v_pk_mul_f32 v[28:29], v[28:29], v[110:111] op_sel_hi:[1,0]
	v_pk_mul_f32 v[30:31], v[228:229], v[30:31]
	v_pk_mul_f32 v[26:27], v[72:73], v[84:85] op_sel_hi:[1,0]
	v_pk_mul_f32 v[6:7], v[228:229], v[24:25]
	v_lshl_add_u64 v[24:25], s[14:15], 0, v[68:69]
	v_pk_mul_f32 v[44:45], v[226:227], v[44:45]
	v_pk_mul_f32 v[28:29], v[226:227], v[28:29]
	v_pk_mul_f32 v[4:5], v[226:227], v[26:27]
	v_lshl_add_u64 v[24:25], v[24:25], 0, v[64:65]
	global_store_dwordx4 v[58:59], v[44:47], off
	global_store_dwordx4 v[40:41], v[28:31], off
	global_store_dwordx4 v[24:25], v[4:7], off
	v_lshl_add_u64 v[64:65], s[14:15], 0, v[64:65]
	v_pk_mul_f32 v[28:29], v[116:117], v[168:169] op_sel_hi:[1,0]
	v_pk_mul_f32 v[4:5], v[70:71], v[84:85] op_sel_hi:[1,0]
	v_pk_mul_f32 v[6:7], v[74:75], v[84:85] op_sel_hi:[1,0]
	v_pk_mul_f32 v[2:3], v[232:233], v[4:5]
	v_pk_mul_f32 v[0:1], v[230:231], v[6:7]
	global_store_dwordx4 v[24:25], v[0:3], off offset:16
	v_pk_mul_f32 v[24:25], v[118:119], v[168:169] op_sel_hi:[1,0]
	v_pk_mul_f32 v[40:41], v[112:113], v[168:169] op_sel_hi:[1,0]
	v_lshl_add_u64 v[66:67], v[64:65], 0, v[76:77]
	v_pk_mul_f32 v[30:31], v[114:115], v[168:169] op_sel_hi:[1,0]
	v_pk_mul_f32 v[42:43], v[102:103], v[166:167] op_sel_hi:[1,0]
	v_pk_mul_f32 v[44:45], v[100:101], v[166:167] op_sel_hi:[1,0]
	v_pk_mul_f32 v[46:47], v[98:99], v[166:167] op_sel_hi:[1,0]
	v_pk_mul_f32 v[56:57], v[96:97], v[166:167] op_sel_hi:[1,0]
	v_pk_mul_f32 v[58:59], v[88:89], v[86:87] op_sel_hi:[1,0]
	v_pk_mul_f32 v[60:61], v[90:91], v[86:87] op_sel_hi:[1,0]
	v_pk_mul_f32 v[62:63], v[92:93], v[86:87] op_sel_hi:[1,0]
	v_pk_mul_f32 v[74:75], v[94:95], v[86:87] op_sel_hi:[1,0]
	v_lshl_add_u64 v[70:71], v[64:65], 0, v[78:79]
	v_lshl_add_u64 v[72:73], v[64:65], 0, v[82:83]
	v_pk_mul_f32 v[22:23], v[22:23], v[110:111] op_sel_hi:[1,0]
	v_pk_mul_f32 v[20:21], v[20:21], v[110:111] op_sel_hi:[1,0]
	v_pk_mul_f32 v[18:19], v[18:19], v[110:111] op_sel_hi:[1,0]
	v_pk_mul_f32 v[16:17], v[16:17], v[110:111] op_sel_hi:[1,0]
	v_pk_mul_f32 v[26:27], v[236:237], v[24:25]
	v_pk_mul_f32 v[24:25], v[234:235], v[28:29]
	v_pk_mul_f32 v[28:29], v[238:239], v[40:41]
	v_pk_mul_f32 v[30:31], v[240:241], v[30:31]
	v_pk_mul_f32 v[42:43], v[236:237], v[42:43]
	v_pk_mul_f32 v[40:41], v[234:235], v[44:45]
	v_pk_mul_f32 v[46:47], v[240:241], v[46:47]
	v_pk_mul_f32 v[44:45], v[238:239], v[56:57]
	v_pk_mul_f32 v[58:59], v[236:237], v[58:59]
	v_pk_mul_f32 v[56:57], v[234:235], v[60:61]
	v_pk_mul_f32 v[62:63], v[240:241], v[62:63]
	v_pk_mul_f32 v[60:61], v[238:239], v[74:75]
	global_store_dwordx4 v[66:67], v[24:27], off offset:512
	global_store_dwordx4 v[66:67], v[28:31], off offset:528
	global_store_dwordx4 v[70:71], v[40:43], off offset:512
	global_store_dwordx4 v[70:71], v[44:47], off offset:528
	global_store_dwordx4 v[72:73], v[56:59], off offset:512
	global_store_dwordx4 v[72:73], v[60:63], off offset:528
	v_pk_mul_f32 v[24:25], v[128:129], v[104:105] op_sel_hi:[1,0]
	v_pk_mul_f32 v[28:29], v[132:133], v[104:105] op_sel_hi:[1,0]
	v_pk_mul_f32 v[26:27], v[236:237], v[24:25]
	v_pk_mul_f32 v[24:25], v[234:235], v[28:29]
	v_lshl_add_u64 v[28:29], v[64:65], 0, v[80:81]
	global_store_dwordx4 v[28:29], v[24:27], off offset:512
	v_pk_mul_f32 v[30:31], v[134:135], v[104:105] op_sel_hi:[1,0]
	v_pk_mul_f32 v[22:23], v[236:237], v[22:23]
	v_pk_mul_f32 v[24:25], v[130:131], v[104:105] op_sel_hi:[1,0]
	v_pk_mul_f32 v[20:21], v[234:235], v[20:21]
	v_pk_mul_f32 v[26:27], v[240:241], v[24:25]
	v_pk_mul_f32 v[24:25], v[238:239], v[30:31]
	global_store_dwordx4 v[28:29], v[24:27], off offset:528
	v_lshl_add_u64 v[28:29], v[64:65], 0, v[194:195]
	v_pk_mul_f32 v[30:31], v[32:33], v[108:109] op_sel_hi:[1,0]
	v_pk_mul_f32 v[24:25], v[52:53], v[200:201] op_sel_hi:[1,0]
	v_pk_mul_f32 v[26:27], v[54:55], v[200:201] op_sel_hi:[1,0]
	v_pk_mul_f32 v[24:25], v[234:235], v[24:25]
	v_pk_mul_f32 v[26:27], v[236:237], v[26:27]
	global_store_dwordx4 v[28:29], v[24:27], off offset:512
	v_pk_mul_f32 v[18:19], v[240:241], v[18:19]
	v_pk_mul_f32 v[16:17], v[238:239], v[16:17]
	v_pk_mul_f32 v[24:25], v[48:49], v[200:201] op_sel_hi:[1,0]
	v_pk_mul_f32 v[26:27], v[50:51], v[200:201] op_sel_hi:[1,0]
	v_pk_mul_f32 v[24:25], v[238:239], v[24:25]
	v_pk_mul_f32 v[26:27], v[240:241], v[26:27]
	global_store_dwordx4 v[28:29], v[24:27], off offset:528
	v_pk_mul_f32 v[28:29], v[36:37], v[108:109] op_sel_hi:[1,0]
	s_nop 0
	v_pk_mul_f32 v[24:25], v[38:39], v[108:109] op_sel_hi:[1,0]
	s_nop 0
	v_pk_mul_f32 v[26:27], v[236:237], v[24:25]
	v_pk_mul_f32 v[24:25], v[234:235], v[28:29]
	v_lshl_add_u64 v[28:29], v[64:65], 0, v[106:107]
	global_store_dwordx4 v[28:29], v[24:27], off offset:512
	v_pk_mul_f32 v[2:3], v[236:237], v[10:11]
	v_pk_mul_f32 v[0:1], v[234:235], v[14:15]
	v_pk_mul_f32 v[24:25], v[34:35], v[108:109] op_sel_hi:[1,0]
	v_lshl_add_u64 v[10:11], v[64:65], 0, v[68:69]
	v_pk_mul_f32 v[26:27], v[240:241], v[24:25]
	v_pk_mul_f32 v[24:25], v[238:239], v[30:31]
	global_store_dwordx4 v[28:29], v[24:27], off offset:528
	s_nop 1
	v_lshl_add_u64 v[24:25], v[64:65], 0, v[120:121]
	global_store_dwordx4 v[24:25], v[20:23], off offset:512
	global_store_dwordx4 v[10:11], v[0:3], off offset:512
	global_store_dwordx4 v[24:25], v[16:19], off offset:528
	s_nop 0
	v_pk_mul_f32 v[0:1], v[8:9], v[84:85] op_sel_hi:[1,0]
	v_pk_mul_f32 v[8:9], v[12:13], v[84:85] op_sel_hi:[1,0]
	v_pk_mul_f32 v[2:3], v[240:241], v[0:1]
	v_pk_mul_f32 v[0:1], v[238:239], v[8:9]
	global_store_dwordx4 v[10:11], v[0:3], off offset:528
	s_waitcnt lgkmcnt(0)
	s_barrier
	s_cbranch_vccnz .LBB0_872
	s_andn2_b64 vcc, exec, s[18:19]
	s_cbranch_vccnz .LBB0_871
	s_barrier
	s_branch .LBB0_871
